# kernel prologue: kernarg scalar loads batched (8 serialized round trips -> 2)
# baseline (speedup 1.0000x reference)
_Z6k_mega6Params:
	s_load_dwordx16 s[40:55], s[0:1], 0x240
	s_load_dword s3, s[0:1], 0x288
	s_load_dwordx2 s[38:39], s[0:1], 0x280
	s_load_dwordx16 s[12:27], s[0:1], 0x40
	s_load_dwordx16 s[56:71], s[0:1], 0x80
	s_load_dwordx16 s[72:87], s[0:1], 0xc0
	s_add_u32 s8, s0, 0x280
	s_addc_u32 s9, s1, 0
	v_and_b32_e32 v136, 0x3ff, v0
	s_waitcnt lgkmcnt(0)
	v_writelane_b32 v253, s3, 0
	v_cmp_eq_u32_e64 s[6:7], 0, v136
	s_mov_b64 s[4:5], exec
	s_nop 0
	v_writelane_b32 v253, s6, 1
	s_nop 1
	v_writelane_b32 v253, s7, 2
	s_and_b64 s[6:7], s[4:5], s[6:7]
	s_mov_b64 exec, s[6:7]
	s_cbranch_execz .LBB0_2
	s_add_i32 s3, 0, 0x20000
	v_mov_b32_e32 v1, 0
	v_mov_b32_e32 v2, s3
	s_add_i32 s3, 0, 0x20004
	ds_write_b32 v2, v1
	v_mov_b32_e32 v2, s3
	s_add_i32 s3, 0, 0x20008
	ds_write_b32 v2, v1
	v_mov_b32_e32 v2, s3
	s_add_i32 s3, 0, 0x2000c
	ds_write_b32 v2, v1
	v_mov_b32_e32 v2, s3
	ds_write_b32 v2, v1
.LBB0_2:
	s_or_b64 exec, exec, s[4:5]

	s_waitcnt lgkmcnt(0)
	s_barrier
	s_getreg_b32 s3, hwreg(HW_REG_XCC_ID, 0, 4)
	v_writelane_b32 v253, s12, 3
	s_and_b32 s3, s3, 15
	s_nop 0
	v_writelane_b32 v253, s13, 4
	v_writelane_b32 v253, s14, 5
	v_writelane_b32 v253, s15, 6
	v_writelane_b32 v253, s16, 7
	v_writelane_b32 v253, s17, 8
	v_writelane_b32 v253, s18, 9
	v_writelane_b32 v253, s19, 10
	v_writelane_b32 v253, s20, 11
	v_writelane_b32 v253, s21, 12
	v_writelane_b32 v253, s22, 13
	v_writelane_b32 v253, s23, 14
	v_writelane_b32 v253, s24, 15
	v_writelane_b32 v253, s25, 16
	v_writelane_b32 v253, s26, 17
	v_writelane_b32 v253, s27, 18


	v_writelane_b32 v253, s56, 19
	s_nop 1
	v_writelane_b32 v253, s57, 20
	v_writelane_b32 v253, s58, 21
	v_writelane_b32 v253, s59, 22
	v_writelane_b32 v253, s60, 23
	v_writelane_b32 v253, s61, 24
	v_writelane_b32 v253, s62, 25
	v_writelane_b32 v253, s63, 26
	v_writelane_b32 v253, s64, 27
	v_writelane_b32 v253, s65, 28
	v_writelane_b32 v253, s66, 29
	v_writelane_b32 v253, s67, 30
	v_writelane_b32 v253, s68, 31
	v_writelane_b32 v253, s69, 32
	v_writelane_b32 v253, s70, 33
	v_writelane_b32 v253, s71, 34


	v_writelane_b32 v253, s72, 35
	s_nop 1
	v_writelane_b32 v253, s73, 36
	v_writelane_b32 v253, s74, 37
	v_writelane_b32 v253, s75, 38
	v_writelane_b32 v253, s76, 39
	v_writelane_b32 v253, s77, 40
	v_writelane_b32 v253, s78, 41
	v_writelane_b32 v253, s79, 42
	v_writelane_b32 v253, s80, 43
	v_writelane_b32 v253, s81, 44
	v_writelane_b32 v253, s82, 45
	v_writelane_b32 v253, s83, 46
	v_writelane_b32 v253, s84, 47
	v_writelane_b32 v253, s85, 48
	v_writelane_b32 v253, s86, 49
	v_writelane_b32 v253, s87, 50
	s_load_dwordx16 s[56:71], s[0:1], 0x140
	s_load_dwordx16 s[72:87], s[0:1], 0x180
	s_load_dwordx8 s[28:35], s[0:1], 0x200
	s_load_dwordx8 s[88:95], s[0:1], 0x220
	s_load_dwordx16 s[12:27], s[0:1], 0x0
	s_waitcnt lgkmcnt(0)
	v_writelane_b32 v253, s56, 51
	s_nop 1
	v_writelane_b32 v253, s57, 52
	v_writelane_b32 v253, s58, 53
	v_writelane_b32 v253, s59, 54
	v_writelane_b32 v253, s60, 55
	v_writelane_b32 v253, s61, 56
	v_writelane_b32 v253, s62, 57
	v_writelane_b32 v253, s63, 58
	v_writelane_b32 v253, s64, 59
	v_writelane_b32 v253, s65, 60
	v_writelane_b32 v253, s66, 61
	v_writelane_b32 v254, s69, 0
	v_writelane_b32 v253, s67, 62
	v_writelane_b32 v254, s70, 1
	v_writelane_b32 v253, s68, 63
	v_writelane_b32 v254, s71, 2

	v_writelane_b32 v254, s3, 3

	v_writelane_b32 v254, s72, 4
	s_nop 1
	v_writelane_b32 v254, s73, 5
	v_writelane_b32 v254, s74, 6
	v_writelane_b32 v254, s75, 7
	v_writelane_b32 v254, s76, 8
	v_writelane_b32 v254, s77, 9
	v_writelane_b32 v254, s78, 10
	v_writelane_b32 v254, s79, 11
	v_writelane_b32 v254, s80, 12
	v_writelane_b32 v254, s81, 13
	v_writelane_b32 v254, s82, 14
	v_writelane_b32 v254, s83, 15
	v_writelane_b32 v254, s84, 16
	v_writelane_b32 v254, s85, 17
	v_writelane_b32 v254, s86, 18
	v_writelane_b32 v254, s87, 19


	v_writelane_b32 v254, s28, 20
	s_nop 1
	v_writelane_b32 v254, s29, 21
	v_writelane_b32 v254, s30, 22
	v_writelane_b32 v254, s31, 23
	v_writelane_b32 v254, s32, 24
	v_writelane_b32 v254, s33, 25
	v_writelane_b32 v254, s34, 26
	v_writelane_b32 v254, s35, 27
	v_writelane_b32 v254, s88, 28
	v_writelane_b32 v254, s89, 29
	v_writelane_b32 v254, s90, 30
	v_writelane_b32 v254, s91, 31
	v_writelane_b32 v254, s92, 32
	v_writelane_b32 v254, s93, 33
	v_writelane_b32 v254, s94, 34
	v_writelane_b32 v254, s95, 35
	s_mov_b64 s[4:5], exec
	v_readlane_b32 s6, v253, 1
	v_readlane_b32 s7, v253, 2
	s_and_b64 s[6:7], s[4:5], s[6:7]
	s_mov_b64 exec, s[6:7]
	s_cbranch_execz .LBB0_5
	s_mov_b64 s[6:7], exec
	v_mbcnt_lo_u32_b32 v1, s6, 0
	v_mbcnt_hi_u32_b32 v1, s7, v1
	v_cmp_eq_u32_e32 vcc, 0, v1
	s_and_b64 s[10:11], exec, vcc
	s_mov_b64 exec, s[10:11]
	s_cbranch_execz .LBB0_5
	v_readlane_b32 s3, v254, 3
	s_lshl_b32 s3, s3, 8
	s_bcnt1_i32_b64 s6, s[6:7]
	v_mov_b32_e32 v1, s3
	v_mov_b32_e32 v2, s6
	global_atomic_add v1, v2, s[54:55] offset:1024
.LBB0_5:
	s_or_b64 exec, exec, s[4:5]

	s_cmp_gt_u32 s2, 31
	s_mov_b64 s[4:5], -1
	s_waitcnt lgkmcnt(0)
	v_writelane_b32 v254, s12, 36
	s_nop 1
	v_writelane_b32 v254, s13, 37
	v_writelane_b32 v254, s14, 38
	v_writelane_b32 v254, s15, 39
	v_writelane_b32 v254, s16, 40
	v_writelane_b32 v254, s17, 41
	v_writelane_b32 v254, s18, 42
	v_writelane_b32 v254, s19, 43
	v_writelane_b32 v254, s20, 44
	v_writelane_b32 v254, s21, 45
	v_writelane_b32 v254, s22, 46
	v_writelane_b32 v254, s23, 47
	v_writelane_b32 v254, s24, 48
	v_writelane_b32 v254, s25, 49
	v_writelane_b32 v254, s26, 50
	v_writelane_b32 v254, s27, 51
	s_cbranch_scc0 .LBB0_76
	s_sub_i32 s3, s2, 32
	s_cmpk_gt_i32 s3, 0x33f
	s_cbranch_scc1 .LBB0_80
	s_load_dwordx16 s[12:27], s[0:1], 0x0
	v_and_b32_e32 v5, 63, v136
	v_mov_b32_e32 v57, 0
	v_lshlrev_b32_e32 v56, 4, v5
	v_lshlrev_b32_e32 v2, 2, v5
	s_waitcnt lgkmcnt(0)
	v_lshl_add_u64 v[58:59], s[16:17], 0, v[56:57]
	s_load_dwordx16 s[12:27], s[0:1], 0x140
	v_lshrrev_b32_e32 v54, 4, v136
	v_lshlrev_b32_e32 v1, 2, v136
	v_lshlrev_b32_e32 v6, 3, v136
	v_lshlrev_b32_e32 v64, 2, v2
	v_mbcnt_lo_u32_b32 v2, -1, 0
	v_and_b32_e32 v3, 60, v54
	v_and_b32_e32 v4, 60, v1
	v_lshrrev_b32_e32 v74, 3, v136
	v_and_b32_e32 v6, 56, v6
	s_waitcnt lgkmcnt(0)
	s_add_u32 s10, s20, 0x200000
	v_mbcnt_hi_u32_b32 v79, -1, v2
	v_lshl_add_u32 v7, v4, 2, 0
	v_mul_u32_u24_e32 v8, 0x104, v54
	v_mul_u32_u24_e32 v9, 0x104, v6
	v_lshlrev_b32_e32 v10, 2, v74
	v_lshlrev_b32_e32 v56, 3, v5
	s_addc_u32 s11, s21, 0
	v_lshl_add_u32 v3, s2, 5, v3
	s_lshl_b32 s29, s38, 5
	v_and_b32_e32 v2, 64, v79
	v_cmp_eq_u32_e64 s[4:5], 0, v5
	v_add_u32_e32 v1, 32, v54
	v_or_b32_e32 v75, 0xfffffc80, v74
	v_add3_u32 v76, 0, v9, v10
	v_lshl_add_u64 v[60:61], s[16:17], 0, v[56:57]
	v_lshl_add_u64 v[62:63], s[14:15], 0, v[56:57]
	s_sub_i32 s26, s38, 32
	v_mov_b32_e32 v55, v57
	s_movk_i32 s27, 0xff00
	s_add_i32 s28, s2, 0xffffff00
	v_add_u32_e32 v56, 0xffffde00, v3
	s_addk_i32 s29, 0xfc00
	v_mov_b32_e32 v77, 0x358637bd
	s_mov_b32 s30, 0x800000
	v_lshlrev_b32_e32 v66, 2, v4
	v_add_u32_e32 v78, v7, v8
	s_movk_i32 s31, 0x1ff
	v_lshlrev_b32_e32 v68, 1, v6
	v_add_u32_e32 v80, 64, v2
	v_xor_b32_e32 v81, 32, v79
	v_xor_b32_e32 v82, 16, v79
	v_xor_b32_e32 v83, 8, v79
	v_xor_b32_e32 v84, 4, v79
	v_xor_b32_e32 v85, 2, v79
	v_xor_b32_e32 v86, 1, v79
	s_branch .LBB0_11
